# dwordx2-per-lane knorm (v56 layout) with trip-dependent exact vmcnt (10 steady, 6 first/last); bit-identical
# speedup vs baseline: 1.0027x; 1.0027x over previous
; __device__ __forceinline__ float bf2f(unsigned short u) { return __uint_as_float((unsigned)u << 16); }
; __device__ __forceinline__ unsigned f2bf(float f) { unsigned u = __float_as_uint(f); return (u + 0x7fffu + ((u >> 16) & 1u)) >> 16; }
; __device__ __forceinline__ void knorm_item(const KArgs& a, int l, int item, int wave, int lane) {
;     const bf16_t* Z = (const bf16_t*)(a.ws + WS_Z);
;     const float kg = a.in[I_KN][l * 64 + lane];
;     for (int r0 = 0; r0 < 128; r0 += 16) {
;         float v[16];
; #pragma unroll
;         for (int i = 0; i < 16; ++i) { const int task = item * 1024 + wave * 128 + r0 + i, row = task >> 2, which = (task >> 1) & 1, g = task & 1;
;             v[i] = bf2f(Z[(size_t)row * ZW + (which ? ZC_KW : ZC_KS) + g * 64 + lane]); }
; #pragma unroll
;         for (int i = 0; i < 16; ++i) { const int task = item * 1024 + wave * 128 + r0 + i, row = task >> 2, which = (task >> 1) & 1, g = task & 1;
;             const float rstd = rsqrtf(wave_sum(v[i] * v[i]) * (1.f / 64.f) + EPS);
;             bf16_t* dst = (bf16_t*)(a.ws + (which ? WS_KWN : WS_KSN));
;             dst[(size_t)row * 128 + g * 64 + lane] = (bf16_t)f2bf(v[i] * rstd * kg); }
;     }
; }
.LBB0_237:
	s_add_i32 s0, s24, s57
	s_add_i32 s0, s0, 0xfff80020
	s_ashr_i32 s4, s0, 2
	s_ashr_i32 s5, s4, 31
	s_mul_i32 s0, s4, 0x1a00
	s_mul_hi_i32 s1, s4, 0x1a00
	s_add_u32 s0, s92, s0
	s_addc_u32 s1, s93, s1
	v_lshl_add_u64 v[0:1], s[0:1], 0, v[192:193]
	global_load_dwordx2 v[24:25], v[0:1], off offset:1024
	s_add_u32 s0, s0, 0x1a00
	s_addc_u32 s1, s1, 0
	v_lshl_add_u64 v[2:3], s[0:1], 0, v[192:193]
	global_load_dwordx2 v[26:27], v[2:3], off offset:1024
	s_add_u32 s0, s0, 0x1a00
	s_addc_u32 s1, s1, 0
	v_lshl_add_u64 v[0:1], s[0:1], 0, v[192:193]
	global_load_dwordx2 v[196:197], v[0:1], off offset:1024
	s_add_u32 s0, s0, 0x1a00
	s_addc_u32 s1, s1, 0
	v_lshl_add_u64 v[2:3], s[0:1], 0, v[192:193]
	global_load_dwordx2 v[198:199], v[2:3], off offset:1024
	s_add_i32 s0, s24, s57
	s_add_i32 s0, s0, 0xfff80010
	s_ashr_i32 s4, s0, 2
	s_ashr_i32 s5, s4, 31
	s_lshl_b64 s[30:31], s[4:5], 8
	v_lshl_add_u64 v[200:201], v[190:191], 0, s[30:31]
	s_cmp_eq_i32 s57, -16
	s_cbranch_scc1 .Lkn6_s_237_0_0
	s_waitcnt vmcnt(10)
	s_branch .Lkn6_e_237_0_0
.Lkn6_s_237_0_0:
	s_waitcnt vmcnt(6)
.Lkn6_e_237_0_0:
	v_lshlrev_b32_e32 v220, 16, v16
	v_and_b32_e32 v221, 0xffff0000, v16
	v_lshlrev_b32_e32 v222, 16, v17
	v_and_b32_e32 v223, 0xffff0000, v17
	v_lshlrev_b32_e32 v236, 16, v18
	v_and_b32_e32 v237, 0xffff0000, v18
	v_lshlrev_b32_e32 v238, 16, v19
	v_and_b32_e32 v239, 0xffff0000, v19
	v_mul_f32_e32 v224, v220, v220
	v_mul_f32_e32 v225, v221, v221
	v_mul_f32_e32 v226, v222, v222
	v_mul_f32_e32 v227, v223, v223
	v_mul_f32_e32 v240, v236, v236
	v_mul_f32_e32 v241, v237, v237
	v_mul_f32_e32 v242, v238, v238
	v_mul_f32_e32 v243, v239, v239
	v_fma_f32 v228, v220, v220, v225
	v_fma_f32 v229, v221, v221, v224
	v_fma_f32 v230, v222, v222, v227
	v_fma_f32 v231, v223, v223, v226
	v_fma_f32 v244, v236, v236, v241
	v_fma_f32 v245, v237, v237, v240
	v_fma_f32 v246, v238, v238, v243
	v_fma_f32 v247, v239, v239, v242
	v_add_f32_e32 v228, v228, v230
	v_add_f32_e32 v229, v229, v231
	v_add_f32_e32 v244, v244, v246
	v_add_f32_e32 v245, v245, v247
	v_add_f32_dpp v228, v228, v228 quad_perm:[1,0,3,2] row_mask:0xf bank_mask:0xf
	v_add_f32_dpp v229, v229, v229 quad_perm:[1,0,3,2] row_mask:0xf bank_mask:0xf
	v_add_f32_dpp v244, v244, v244 quad_perm:[1,0,3,2] row_mask:0xf bank_mask:0xf
	v_add_f32_dpp v245, v245, v245 quad_perm:[1,0,3,2] row_mask:0xf bank_mask:0xf
	v_add_f32_dpp v228, v228, v228 quad_perm:[2,3,0,1] row_mask:0xf bank_mask:0xf
	v_add_f32_dpp v229, v229, v229 quad_perm:[2,3,0,1] row_mask:0xf bank_mask:0xf
	v_add_f32_dpp v244, v244, v244 quad_perm:[2,3,0,1] row_mask:0xf bank_mask:0xf
	v_add_f32_dpp v245, v245, v245 quad_perm:[2,3,0,1] row_mask:0xf bank_mask:0xf
	ds_bpermute_b32 v230, v11, v228
	ds_bpermute_b32 v231, v11, v229
	ds_bpermute_b32 v246, v11, v244
	ds_bpermute_b32 v247, v11, v245
	s_waitcnt lgkmcnt(0)
	v_add_f32_e32 v228, v228, v230
	v_add_f32_e32 v229, v229, v231
	v_add_f32_e32 v244, v244, v246
	v_add_f32_e32 v245, v245, v247
	v_add_f32_dpp v228, v228, v228 row_ror:8 row_mask:0xf bank_mask:0xf
	v_add_f32_dpp v229, v229, v229 row_ror:8 row_mask:0xf bank_mask:0xf
	v_add_f32_dpp v244, v244, v244 row_ror:8 row_mask:0xf bank_mask:0xf
	v_add_f32_dpp v245, v245, v245 row_ror:8 row_mask:0xf bank_mask:0xf
	v_fma_f32 v228, v228, s22, v195
	v_fma_f32 v229, v229, s22, v195
	v_fma_f32 v244, v244, s22, v195
	v_fma_f32 v245, v245, s22, v195
	v_mul_f32_e32 v232, 0x4b800000, v228
	v_mul_f32_e32 v233, 0x4b800000, v229
	v_cmp_gt_f32_e64 s[4:5], s48, v228
	v_cmp_gt_f32_e32 vcc, s48, v229
	s_nop 1
	v_cndmask_b32_e64 v228, v228, v232, s[4:5]
	v_cndmask_b32_e32 v229, v229, v233, vcc
	v_rsq_f32_e32 v228, v228
	v_rsq_f32_e32 v229, v229
	s_nop 0
	v_mul_f32_e32 v232, 0x45800000, v228
	v_mul_f32_e32 v233, 0x45800000, v229
	v_cndmask_b32_e64 v228, v228, v232, s[4:5]
	v_cndmask_b32_e32 v229, v229, v233, vcc
	v_mul_f32_e32 v220, v228, v220
	v_mul_f32_e32 v221, v229, v221
	v_mul_f32_e32 v222, v228, v222
	v_mul_f32_e32 v223, v229, v223
	v_mul_f32_e32 v220, v184, v220
	v_mul_f32_e32 v221, v185, v221
	v_mul_f32_e32 v222, v186, v222
	v_mul_f32_e32 v223, v187, v223
	v_bfe_u32 v224, v220, 16, 1
	v_bfe_u32 v225, v221, 16, 1
	v_bfe_u32 v226, v222, 16, 1
	v_bfe_u32 v227, v223, 16, 1
	v_add3_u32 v220, v220, v224, s49
	v_add3_u32 v221, v221, v225, s49
	v_add3_u32 v222, v222, v226, s49
	v_add3_u32 v223, v223, v227, s49
	v_perm_b32 v234, v221, v220, v194
	v_perm_b32 v235, v223, v222, v194
	global_store_dwordx2 v[200:201], v[234:235], off
	v_mul_f32_e32 v248, 0x4b800000, v244
	v_mul_f32_e32 v249, 0x4b800000, v245
	v_cmp_gt_f32_e64 s[4:5], s48, v244
	v_cmp_gt_f32_e32 vcc, s48, v245
	s_nop 1
	v_cndmask_b32_e64 v244, v244, v248, s[4:5]
	v_cndmask_b32_e32 v245, v245, v249, vcc
	v_rsq_f32_e32 v244, v244
	v_rsq_f32_e32 v245, v245
	s_nop 0
	v_mul_f32_e32 v248, 0x45800000, v244
	v_mul_f32_e32 v249, 0x45800000, v245
	v_cndmask_b32_e64 v244, v244, v248, s[4:5]
	v_cndmask_b32_e32 v245, v245, v249, vcc
	v_mul_f32_e32 v236, v244, v236
	v_mul_f32_e32 v237, v245, v237
	v_mul_f32_e32 v238, v244, v238
	v_mul_f32_e32 v239, v245, v239
	v_mul_f32_e32 v236, v184, v236
	v_mul_f32_e32 v237, v185, v237
	v_mul_f32_e32 v238, v186, v238
	v_mul_f32_e32 v239, v187, v239
	v_bfe_u32 v240, v236, 16, 1
	v_bfe_u32 v241, v237, 16, 1
	v_bfe_u32 v242, v238, 16, 1
	v_bfe_u32 v243, v239, 16, 1
	v_add3_u32 v236, v236, v240, s49
	v_add3_u32 v237, v237, v241, s49
	v_add3_u32 v238, v238, v242, s49
	v_add3_u32 v239, v239, v243, s49
	v_perm_b32 v250, v237, v236, v194
	v_perm_b32 v251, v239, v238, v194
	global_store_dwordx2 v[200:201], v[250:251], off offset:256
	s_cmp_eq_i32 s57, -16
	s_cbranch_scc1 .Lkn6_s_237_0_1
	s_waitcnt vmcnt(10)
	s_branch .Lkn6_e_237_0_1

; __device__ __forceinline__ float bf2f(unsigned short u) { return __uint_as_float((unsigned)u << 16); }
; __device__ __forceinline__ unsigned f2bf(float f) { unsigned u = __float_as_uint(f); return (u + 0x7fffu + ((u >> 16) & 1u)) >> 16; }
; __device__ __forceinline__ void knorm_item(const KArgs& a, int l, int item, int wave, int lane) {
;     ...
;     for (int r0 = 0; r0 < 128; r0 += 16) {
;         float v[16];
; #pragma unroll
;         for (int i = 0; i < 16; ++i) { const int task = item * 1024 + wave * 128 + r0 + i, row = task >> 2, which = (task >> 1) & 1, g = task & 1;
;             v[i] = bf2f(Z[(size_t)row * ZW + (which ? ZC_KW : ZC_KS) + g * 64 + lane]); }
; #pragma unroll
;         for (int i = 0; i < 16; ++i) { const int task = item * 1024 + wave * 128 + r0 + i, row = task >> 2, which = (task >> 1) & 1, g = task & 1;
;             const float rstd = rsqrtf(wave_sum(v[i] * v[i]) * (1.f / 64.f) + EPS);
;             bf16_t* dst = (bf16_t*)(a.ws + (which ? WS_KWN : WS_KSN));
;             dst[(size_t)row * 128 + g * 64 + lane] = (bf16_t)f2bf(v[i] * rstd * kg); }
.Lkn6_e_237_0_1:
	v_lshlrev_b32_e32 v220, 16, v20
	v_and_b32_e32 v221, 0xffff0000, v20
	v_lshlrev_b32_e32 v222, 16, v21
	v_and_b32_e32 v223, 0xffff0000, v21
	v_lshlrev_b32_e32 v236, 16, v22
	v_and_b32_e32 v237, 0xffff0000, v22
	v_lshlrev_b32_e32 v238, 16, v23
	v_and_b32_e32 v239, 0xffff0000, v23
	v_mul_f32_e32 v224, v220, v220
	v_mul_f32_e32 v225, v221, v221
	v_mul_f32_e32 v226, v222, v222
	v_mul_f32_e32 v227, v223, v223
	v_mul_f32_e32 v240, v236, v236
	v_mul_f32_e32 v241, v237, v237
	v_mul_f32_e32 v242, v238, v238
	v_mul_f32_e32 v243, v239, v239
	v_fma_f32 v228, v220, v220, v225
	v_fma_f32 v229, v221, v221, v224
	v_fma_f32 v230, v222, v222, v227
	v_fma_f32 v231, v223, v223, v226
	v_fma_f32 v244, v236, v236, v241
	v_fma_f32 v245, v237, v237, v240
	v_fma_f32 v246, v238, v238, v243
	v_fma_f32 v247, v239, v239, v242
	v_add_f32_e32 v228, v228, v230
	v_add_f32_e32 v229, v229, v231
	v_add_f32_e32 v244, v244, v246
	v_add_f32_e32 v245, v245, v247
	v_add_f32_dpp v228, v228, v228 quad_perm:[1,0,3,2] row_mask:0xf bank_mask:0xf
	v_add_f32_dpp v229, v229, v229 quad_perm:[1,0,3,2] row_mask:0xf bank_mask:0xf
	v_add_f32_dpp v244, v244, v244 quad_perm:[1,0,3,2] row_mask:0xf bank_mask:0xf
	v_add_f32_dpp v245, v245, v245 quad_perm:[1,0,3,2] row_mask:0xf bank_mask:0xf
	v_add_f32_dpp v228, v228, v228 quad_perm:[2,3,0,1] row_mask:0xf bank_mask:0xf
	v_add_f32_dpp v229, v229, v229 quad_perm:[2,3,0,1] row_mask:0xf bank_mask:0xf
	v_add_f32_dpp v244, v244, v244 quad_perm:[2,3,0,1] row_mask:0xf bank_mask:0xf
	v_add_f32_dpp v245, v245, v245 quad_perm:[2,3,0,1] row_mask:0xf bank_mask:0xf
	ds_bpermute_b32 v230, v11, v228
	ds_bpermute_b32 v231, v11, v229
	ds_bpermute_b32 v246, v11, v244
	ds_bpermute_b32 v247, v11, v245
	s_waitcnt lgkmcnt(0)
	v_add_f32_e32 v228, v228, v230
	v_add_f32_e32 v229, v229, v231
	v_add_f32_e32 v244, v244, v246
	v_add_f32_e32 v245, v245, v247
	v_add_f32_dpp v228, v228, v228 row_ror:8 row_mask:0xf bank_mask:0xf
	v_add_f32_dpp v229, v229, v229 row_ror:8 row_mask:0xf bank_mask:0xf
	v_add_f32_dpp v244, v244, v244 row_ror:8 row_mask:0xf bank_mask:0xf
	v_add_f32_dpp v245, v245, v245 row_ror:8 row_mask:0xf bank_mask:0xf
	v_fma_f32 v228, v228, s22, v195
	v_fma_f32 v229, v229, s22, v195
	v_fma_f32 v244, v244, s22, v195
	v_fma_f32 v245, v245, s22, v195
	v_mul_f32_e32 v232, 0x4b800000, v228
	v_mul_f32_e32 v233, 0x4b800000, v229
	v_cmp_gt_f32_e64 s[4:5], s48, v228
	v_cmp_gt_f32_e32 vcc, s48, v229
	s_nop 1
	v_cndmask_b32_e64 v228, v228, v232, s[4:5]
	v_cndmask_b32_e32 v229, v229, v233, vcc
	v_rsq_f32_e32 v228, v228
	v_rsq_f32_e32 v229, v229
	s_nop 0
	v_mul_f32_e32 v232, 0x45800000, v228
	v_mul_f32_e32 v233, 0x45800000, v229
	v_cndmask_b32_e64 v228, v228, v232, s[4:5]
	v_cndmask_b32_e32 v229, v229, v233, vcc
	v_mul_f32_e32 v220, v228, v220
	v_mul_f32_e32 v221, v229, v221
	v_mul_f32_e32 v222, v228, v222
	v_mul_f32_e32 v223, v229, v223
	v_mul_f32_e32 v220, v184, v220
	v_mul_f32_e32 v221, v185, v221
	v_mul_f32_e32 v222, v186, v222
	v_mul_f32_e32 v223, v187, v223
	v_bfe_u32 v224, v220, 16, 1
	v_bfe_u32 v225, v221, 16, 1
	v_bfe_u32 v226, v222, 16, 1
	v_bfe_u32 v227, v223, 16, 1
	v_add3_u32 v220, v220, v224, s49
	v_add3_u32 v221, v221, v225, s49
	v_add3_u32 v222, v222, v226, s49
	v_add3_u32 v223, v223, v227, s49
	v_perm_b32 v234, v221, v220, v194
	v_perm_b32 v235, v223, v222, v194
	global_store_dwordx2 v[200:201], v[234:235], off offset:512
	v_mul_f32_e32 v248, 0x4b800000, v244
	v_mul_f32_e32 v249, 0x4b800000, v245
	v_cmp_gt_f32_e64 s[4:5], s48, v244
	v_cmp_gt_f32_e32 vcc, s48, v245
	s_nop 1
	v_cndmask_b32_e64 v244, v244, v248, s[4:5]
	v_cndmask_b32_e32 v245, v245, v249, vcc
	v_rsq_f32_e32 v244, v244
	v_rsq_f32_e32 v245, v245
	s_nop 0
	v_mul_f32_e32 v248, 0x45800000, v244
	v_mul_f32_e32 v249, 0x45800000, v245
	v_cndmask_b32_e64 v244, v244, v248, s[4:5]
	v_cndmask_b32_e32 v245, v245, v249, vcc
	v_mul_f32_e32 v236, v244, v236
	v_mul_f32_e32 v237, v245, v237
	v_mul_f32_e32 v238, v244, v238
	v_mul_f32_e32 v239, v245, v239
	v_mul_f32_e32 v236, v184, v236
	v_mul_f32_e32 v237, v185, v237
	v_mul_f32_e32 v238, v186, v238
	v_mul_f32_e32 v239, v187, v239
	v_bfe_u32 v240, v236, 16, 1
	v_bfe_u32 v241, v237, 16, 1
	v_bfe_u32 v242, v238, 16, 1
	v_bfe_u32 v243, v239, 16, 1
	v_add3_u32 v236, v236, v240, s49
	v_add3_u32 v237, v237, v241, s49
	v_add3_u32 v238, v238, v242, s49
	v_add3_u32 v239, v239, v243, s49
	v_perm_b32 v250, v237, v236, v194
	v_perm_b32 v251, v239, v238, v194
	global_store_dwordx2 v[200:201], v[250:251], off offset:768
	s_cmpk_gt_i32 s57, 64
	s_cbranch_scc1 .Lkn6_skip_237
	s_add_i32 s0, s24, s57
	s_add_i32 s0, s0, 0xfff80030
	s_ashr_i32 s4, s0, 2
	s_ashr_i32 s5, s4, 31
	s_mul_i32 s0, s4, 0x1a00
	s_mul_hi_i32 s1, s4, 0x1a00
	s_add_u32 s0, s92, s0
	s_addc_u32 s1, s93, s1
	v_lshl_add_u64 v[0:1], s[0:1], 0, v[192:193]
	global_load_dwordx2 v[16:17], v[0:1], off offset:1024
	s_add_u32 s0, s0, 0x1a00
	s_addc_u32 s1, s1, 0
	v_lshl_add_u64 v[2:3], s[0:1], 0, v[192:193]
	global_load_dwordx2 v[18:19], v[2:3], off offset:1024
	s_add_u32 s0, s0, 0x1a00
	s_addc_u32 s1, s1, 0
	v_lshl_add_u64 v[0:1], s[0:1], 0, v[192:193]
	global_load_dwordx2 v[20:21], v[0:1], off offset:1024
	s_add_u32 s0, s0, 0x1a00
	s_addc_u32 s1, s1, 0
	v_lshl_add_u64 v[2:3], s[0:1], 0, v[192:193]
	global_load_dwordx2 v[22:23], v[2:3], off offset:1024
.Lkn6_skip_237:
	s_add_i32 s0, s24, s57
	s_add_i32 s0, s0, 0xfff80020
	s_ashr_i32 s4, s0, 2
	s_ashr_i32 s5, s4, 31
	s_lshl_b64 s[30:31], s[4:5], 8
	v_lshl_add_u64 v[200:201], v[190:191], 0, s[30:31]
	s_cmpk_eq_i32 s57, 0x50
	s_cbranch_scc1 .Lkn6_s_237_1_0
	s_waitcnt vmcnt(10)
	s_branch .Lkn6_e_237_1_0

; __device__ __forceinline__ float bf2f(unsigned short u) { return __uint_as_float((unsigned)u << 16); }
; __device__ __forceinline__ unsigned f2bf(float f) { unsigned u = __float_as_uint(f); return (u + 0x7fffu + ((u >> 16) & 1u)) >> 16; }
; __device__ __forceinline__ void knorm_item(const KArgs& a, int l, int item, int wave, int lane) {
;     ...
;         for (int i = 0; i < 16; ++i) { const int task = item * 1024 + wave * 128 + r0 + i, row = task >> 2, which = (task >> 1) & 1, g = task & 1;
;             v[i] = bf2f(Z[(size_t)row * ZW + (which ? ZC_KW : ZC_KS) + g * 64 + lane]); }
; #pragma unroll
;         for (int i = 0; i < 16; ++i) { const int task = item * 1024 + wave * 128 + r0 + i, row = task >> 2, which = (task >> 1) & 1, g = task & 1;
;             const float rstd = rsqrtf(wave_sum(v[i] * v[i]) * (1.f / 64.f) + EPS);
;             bf16_t* dst = (bf16_t*)(a.ws + (which ? WS_KWN : WS_KSN));
;             dst[(size_t)row * 128 + g * 64 + lane] = (bf16_t)f2bf(v[i] * rstd * kg); }
.Lkn6_e_237_1_0:
	v_lshlrev_b32_e32 v220, 16, v24
	v_and_b32_e32 v221, 0xffff0000, v24
	v_lshlrev_b32_e32 v222, 16, v25
	v_and_b32_e32 v223, 0xffff0000, v25
	v_lshlrev_b32_e32 v236, 16, v26
	v_and_b32_e32 v237, 0xffff0000, v26
	v_lshlrev_b32_e32 v238, 16, v27
	v_and_b32_e32 v239, 0xffff0000, v27
	v_mul_f32_e32 v224, v220, v220
	v_mul_f32_e32 v225, v221, v221
	v_mul_f32_e32 v226, v222, v222
	v_mul_f32_e32 v227, v223, v223
	v_mul_f32_e32 v240, v236, v236
	v_mul_f32_e32 v241, v237, v237
	v_mul_f32_e32 v242, v238, v238
	v_mul_f32_e32 v243, v239, v239
	v_fma_f32 v228, v220, v220, v225
	v_fma_f32 v229, v221, v221, v224
	v_fma_f32 v230, v222, v222, v227
	v_fma_f32 v231, v223, v223, v226
	v_fma_f32 v244, v236, v236, v241
	v_fma_f32 v245, v237, v237, v240
	v_fma_f32 v246, v238, v238, v243
	v_fma_f32 v247, v239, v239, v242
	v_add_f32_e32 v228, v228, v230
	v_add_f32_e32 v229, v229, v231
	v_add_f32_e32 v244, v244, v246
	v_add_f32_e32 v245, v245, v247
	v_add_f32_dpp v228, v228, v228 quad_perm:[1,0,3,2] row_mask:0xf bank_mask:0xf
	v_add_f32_dpp v229, v229, v229 quad_perm:[1,0,3,2] row_mask:0xf bank_mask:0xf
	v_add_f32_dpp v244, v244, v244 quad_perm:[1,0,3,2] row_mask:0xf bank_mask:0xf
	v_add_f32_dpp v245, v245, v245 quad_perm:[1,0,3,2] row_mask:0xf bank_mask:0xf
	v_add_f32_dpp v228, v228, v228 quad_perm:[2,3,0,1] row_mask:0xf bank_mask:0xf
	v_add_f32_dpp v229, v229, v229 quad_perm:[2,3,0,1] row_mask:0xf bank_mask:0xf
	v_add_f32_dpp v244, v244, v244 quad_perm:[2,3,0,1] row_mask:0xf bank_mask:0xf
	v_add_f32_dpp v245, v245, v245 quad_perm:[2,3,0,1] row_mask:0xf bank_mask:0xf
	ds_bpermute_b32 v230, v11, v228
	ds_bpermute_b32 v231, v11, v229
	ds_bpermute_b32 v246, v11, v244
	ds_bpermute_b32 v247, v11, v245
	s_waitcnt lgkmcnt(0)
	v_add_f32_e32 v228, v228, v230
	v_add_f32_e32 v229, v229, v231
	v_add_f32_e32 v244, v244, v246
	v_add_f32_e32 v245, v245, v247
	v_add_f32_dpp v228, v228, v228 row_ror:8 row_mask:0xf bank_mask:0xf
	v_add_f32_dpp v229, v229, v229 row_ror:8 row_mask:0xf bank_mask:0xf
	v_add_f32_dpp v244, v244, v244 row_ror:8 row_mask:0xf bank_mask:0xf
	v_add_f32_dpp v245, v245, v245 row_ror:8 row_mask:0xf bank_mask:0xf
	v_fma_f32 v228, v228, s22, v195
	v_fma_f32 v229, v229, s22, v195
	v_fma_f32 v244, v244, s22, v195
	v_fma_f32 v245, v245, s22, v195
	v_mul_f32_e32 v232, 0x4b800000, v228
	v_mul_f32_e32 v233, 0x4b800000, v229
	v_cmp_gt_f32_e64 s[4:5], s48, v228
	v_cmp_gt_f32_e32 vcc, s48, v229
	s_nop 1
	v_cndmask_b32_e64 v228, v228, v232, s[4:5]
	v_cndmask_b32_e32 v229, v229, v233, vcc
	v_rsq_f32_e32 v228, v228
	v_rsq_f32_e32 v229, v229
	s_nop 0
	v_mul_f32_e32 v232, 0x45800000, v228
	v_mul_f32_e32 v233, 0x45800000, v229
	v_cndmask_b32_e64 v228, v228, v232, s[4:5]
	v_cndmask_b32_e32 v229, v229, v233, vcc
	v_mul_f32_e32 v220, v228, v220
	v_mul_f32_e32 v221, v229, v221
	v_mul_f32_e32 v222, v228, v222
	v_mul_f32_e32 v223, v229, v223
	v_mul_f32_e32 v220, v184, v220
	v_mul_f32_e32 v221, v185, v221
	v_mul_f32_e32 v222, v186, v222
	v_mul_f32_e32 v223, v187, v223
	v_bfe_u32 v224, v220, 16, 1
	v_bfe_u32 v225, v221, 16, 1
	v_bfe_u32 v226, v222, 16, 1
	v_bfe_u32 v227, v223, 16, 1
	v_add3_u32 v220, v220, v224, s49
	v_add3_u32 v221, v221, v225, s49
	v_add3_u32 v222, v222, v226, s49
	v_add3_u32 v223, v223, v227, s49
	v_perm_b32 v234, v221, v220, v194
	v_perm_b32 v235, v223, v222, v194
	global_store_dwordx2 v[200:201], v[234:235], off
	v_mul_f32_e32 v248, 0x4b800000, v244
	v_mul_f32_e32 v249, 0x4b800000, v245
	v_cmp_gt_f32_e64 s[4:5], s48, v244
	v_cmp_gt_f32_e32 vcc, s48, v245
	s_nop 1
	v_cndmask_b32_e64 v244, v244, v248, s[4:5]
	v_cndmask_b32_e32 v245, v245, v249, vcc
	v_rsq_f32_e32 v244, v244
	v_rsq_f32_e32 v245, v245
	s_nop 0
	v_mul_f32_e32 v248, 0x45800000, v244
	v_mul_f32_e32 v249, 0x45800000, v245
	v_cndmask_b32_e64 v244, v244, v248, s[4:5]
	v_cndmask_b32_e32 v245, v245, v249, vcc
	v_mul_f32_e32 v236, v244, v236
	v_mul_f32_e32 v237, v245, v237
	v_mul_f32_e32 v238, v244, v238
	v_mul_f32_e32 v239, v245, v239
	v_mul_f32_e32 v236, v184, v236
	v_mul_f32_e32 v237, v185, v237
	v_mul_f32_e32 v238, v186, v238
	v_mul_f32_e32 v239, v187, v239
	v_bfe_u32 v240, v236, 16, 1
	v_bfe_u32 v241, v237, 16, 1
	v_bfe_u32 v242, v238, 16, 1
	v_bfe_u32 v243, v239, 16, 1
	v_add3_u32 v236, v236, v240, s49
	v_add3_u32 v237, v237, v241, s49
	v_add3_u32 v238, v238, v242, s49
	v_add3_u32 v239, v239, v243, s49
	v_perm_b32 v250, v237, v236, v194
	v_perm_b32 v251, v239, v238, v194
	global_store_dwordx2 v[200:201], v[250:251], off offset:256
	s_cmpk_eq_i32 s57, 0x50
	s_cbranch_scc1 .Lkn6_s_237_1_1
	s_waitcnt vmcnt(10)
	s_branch .Lkn6_e_237_1_1

; __device__ __forceinline__ float bf2f(unsigned short u) { return __uint_as_float((unsigned)u << 16); }
; __device__ __forceinline__ unsigned f2bf(float f) { unsigned u = __float_as_uint(f); return (u + 0x7fffu + ((u >> 16) & 1u)) >> 16; }
; __device__ __forceinline__ void knorm_item(const KArgs& a, int l, int item, int wave, int lane) {
;     ...
;         for (int i = 0; i < 16; ++i) { const int task = item * 1024 + wave * 128 + r0 + i, row = task >> 2, which = (task >> 1) & 1, g = task & 1;
;             v[i] = bf2f(Z[(size_t)row * ZW + (which ? ZC_KW : ZC_KS) + g * 64 + lane]); }
; #pragma unroll
;         for (int i = 0; i < 16; ++i) { const int task = item * 1024 + wave * 128 + r0 + i, row = task >> 2, which = (task >> 1) & 1, g = task & 1;
;             const float rstd = rsqrtf(wave_sum(v[i] * v[i]) * (1.f / 64.f) + EPS);
;             bf16_t* dst = (bf16_t*)(a.ws + (which ? WS_KWN : WS_KSN));
;             dst[(size_t)row * 128 + g * 64 + lane] = (bf16_t)f2bf(v[i] * rstd * kg); }
.Lkn6_e_237_1_1:
	v_lshlrev_b32_e32 v220, 16, v196
	v_and_b32_e32 v221, 0xffff0000, v196
	v_lshlrev_b32_e32 v222, 16, v197
	v_and_b32_e32 v223, 0xffff0000, v197
	v_lshlrev_b32_e32 v236, 16, v198
	v_and_b32_e32 v237, 0xffff0000, v198
	v_lshlrev_b32_e32 v238, 16, v199
	v_and_b32_e32 v239, 0xffff0000, v199
	v_mul_f32_e32 v224, v220, v220
	v_mul_f32_e32 v225, v221, v221
	v_mul_f32_e32 v226, v222, v222
	v_mul_f32_e32 v227, v223, v223
	v_mul_f32_e32 v240, v236, v236
	v_mul_f32_e32 v241, v237, v237
	v_mul_f32_e32 v242, v238, v238
	v_mul_f32_e32 v243, v239, v239
	v_fma_f32 v228, v220, v220, v225
	v_fma_f32 v229, v221, v221, v224
	v_fma_f32 v230, v222, v222, v227
	v_fma_f32 v231, v223, v223, v226
	v_fma_f32 v244, v236, v236, v241
	v_fma_f32 v245, v237, v237, v240
	v_fma_f32 v246, v238, v238, v243
	v_fma_f32 v247, v239, v239, v242
	v_add_f32_e32 v228, v228, v230
	v_add_f32_e32 v229, v229, v231
	v_add_f32_e32 v244, v244, v246
	v_add_f32_e32 v245, v245, v247
	v_add_f32_dpp v228, v228, v228 quad_perm:[1,0,3,2] row_mask:0xf bank_mask:0xf
	v_add_f32_dpp v229, v229, v229 quad_perm:[1,0,3,2] row_mask:0xf bank_mask:0xf
	v_add_f32_dpp v244, v244, v244 quad_perm:[1,0,3,2] row_mask:0xf bank_mask:0xf
	v_add_f32_dpp v245, v245, v245 quad_perm:[1,0,3,2] row_mask:0xf bank_mask:0xf
	v_add_f32_dpp v228, v228, v228 quad_perm:[2,3,0,1] row_mask:0xf bank_mask:0xf
	v_add_f32_dpp v229, v229, v229 quad_perm:[2,3,0,1] row_mask:0xf bank_mask:0xf
	v_add_f32_dpp v244, v244, v244 quad_perm:[2,3,0,1] row_mask:0xf bank_mask:0xf
	v_add_f32_dpp v245, v245, v245 quad_perm:[2,3,0,1] row_mask:0xf bank_mask:0xf
	ds_bpermute_b32 v230, v11, v228
	ds_bpermute_b32 v231, v11, v229
	ds_bpermute_b32 v246, v11, v244
	ds_bpermute_b32 v247, v11, v245
	s_waitcnt lgkmcnt(0)
	v_add_f32_e32 v228, v228, v230
	v_add_f32_e32 v229, v229, v231
	v_add_f32_e32 v244, v244, v246
	v_add_f32_e32 v245, v245, v247
	v_add_f32_dpp v228, v228, v228 row_ror:8 row_mask:0xf bank_mask:0xf
	v_add_f32_dpp v229, v229, v229 row_ror:8 row_mask:0xf bank_mask:0xf
	v_add_f32_dpp v244, v244, v244 row_ror:8 row_mask:0xf bank_mask:0xf
	v_add_f32_dpp v245, v245, v245 row_ror:8 row_mask:0xf bank_mask:0xf
	v_fma_f32 v228, v228, s22, v195
	v_fma_f32 v229, v229, s22, v195
	v_fma_f32 v244, v244, s22, v195
	v_fma_f32 v245, v245, s22, v195
	v_mul_f32_e32 v232, 0x4b800000, v228
	v_mul_f32_e32 v233, 0x4b800000, v229
	v_cmp_gt_f32_e64 s[4:5], s48, v228
	v_cmp_gt_f32_e32 vcc, s48, v229
	s_nop 1
	v_cndmask_b32_e64 v228, v228, v232, s[4:5]
	v_cndmask_b32_e32 v229, v229, v233, vcc
	v_rsq_f32_e32 v228, v228
	v_rsq_f32_e32 v229, v229
	s_nop 0
	v_mul_f32_e32 v232, 0x45800000, v228
	v_mul_f32_e32 v233, 0x45800000, v229
	v_cndmask_b32_e64 v228, v228, v232, s[4:5]
	v_cndmask_b32_e32 v229, v229, v233, vcc
	v_mul_f32_e32 v220, v228, v220
	v_mul_f32_e32 v221, v229, v221
	v_mul_f32_e32 v222, v228, v222
	v_mul_f32_e32 v223, v229, v223
	v_mul_f32_e32 v220, v184, v220
	v_mul_f32_e32 v221, v185, v221
	v_mul_f32_e32 v222, v186, v222
	v_mul_f32_e32 v223, v187, v223
	v_bfe_u32 v224, v220, 16, 1
	v_bfe_u32 v225, v221, 16, 1
	v_bfe_u32 v226, v222, 16, 1
	v_bfe_u32 v227, v223, 16, 1
	v_add3_u32 v220, v220, v224, s49
	v_add3_u32 v221, v221, v225, s49
	v_add3_u32 v222, v222, v226, s49
	v_add3_u32 v223, v223, v227, s49
	v_perm_b32 v234, v221, v220, v194
	v_perm_b32 v235, v223, v222, v194
	global_store_dwordx2 v[200:201], v[234:235], off offset:512
	v_mul_f32_e32 v248, 0x4b800000, v244
	v_mul_f32_e32 v249, 0x4b800000, v245
	v_cmp_gt_f32_e64 s[4:5], s48, v244
	v_cmp_gt_f32_e32 vcc, s48, v245
	s_nop 1
	v_cndmask_b32_e64 v244, v244, v248, s[4:5]
	v_cndmask_b32_e32 v245, v245, v249, vcc
	v_rsq_f32_e32 v244, v244
	v_rsq_f32_e32 v245, v245
	s_nop 0
	v_mul_f32_e32 v248, 0x45800000, v244
	v_mul_f32_e32 v249, 0x45800000, v245
	v_cndmask_b32_e64 v244, v244, v248, s[4:5]
	v_cndmask_b32_e32 v245, v245, v249, vcc
	v_mul_f32_e32 v236, v244, v236
	v_mul_f32_e32 v237, v245, v237
	v_mul_f32_e32 v238, v244, v238
	v_mul_f32_e32 v239, v245, v239
	v_mul_f32_e32 v236, v184, v236
	v_mul_f32_e32 v237, v185, v237
	v_mul_f32_e32 v238, v186, v238
	v_mul_f32_e32 v239, v187, v239
	v_bfe_u32 v240, v236, 16, 1
	v_bfe_u32 v241, v237, 16, 1
	v_bfe_u32 v242, v238, 16, 1
	v_bfe_u32 v243, v239, 16, 1
	v_add3_u32 v236, v236, v240, s49
	v_add3_u32 v237, v237, v241, s49
	v_add3_u32 v238, v238, v242, s49
	v_add3_u32 v239, v239, v243, s49
	v_perm_b32 v250, v237, v236, v194
	v_perm_b32 v251, v239, v238, v194
	global_store_dwordx2 v[200:201], v[250:251], off offset:768
	s_add_i32 s57, s57, 32
	s_cmpk_gt_u32 s57, 0x6f
	s_cbranch_scc0 .LBB0_237
	s_mov_b64 s[0:1], 0

; __device__ __forceinline__ float bf2f(unsigned short u) { return __uint_as_float((unsigned)u << 16); }
; __device__ __forceinline__ void knorm_item(const KArgs& a, int l, int item, int wave, int lane) {
;     ...
;     for (int r0 = 0; r0 < 128; r0 += 16) {
;         float v[16];
; #pragma unroll
;         for (int i = 0; i < 16; ++i) { const int task = item * 1024 + wave * 128 + r0 + i, row = task >> 2, which = (task >> 1) & 1, g = task & 1;
;             v[i] = bf2f(Z[(size_t)row * ZW + (which ? ZC_KW : ZC_KS) + g * 64 + lane]); }
.LBB0_1038:
	s_add_i32 s0, s30, s63
	s_add_i32 s0, s0, 0xfff80020
	s_ashr_i32 s4, s0, 2
	s_ashr_i32 s5, s4, 31
	s_mul_i32 s0, s4, 0x1a00
	s_mul_hi_i32 s1, s4, 0x1a00
	s_add_u32 s0, s92, s0
	s_addc_u32 s1, s93, s1
	v_lshl_add_u64 v[0:1], s[0:1], 0, v[192:193]
	global_load_dwordx2 v[24:25], v[0:1], off offset:1024
	s_add_u32 s0, s0, 0x1a00
	s_addc_u32 s1, s1, 0
	v_lshl_add_u64 v[2:3], s[0:1], 0, v[192:193]
	global_load_dwordx2 v[26:27], v[2:3], off offset:1024
	s_add_u32 s0, s0, 0x1a00
	s_addc_u32 s1, s1, 0
	v_lshl_add_u64 v[0:1], s[0:1], 0, v[192:193]
	global_load_dwordx2 v[196:197], v[0:1], off offset:1024
	s_add_u32 s0, s0, 0x1a00
	s_addc_u32 s1, s1, 0
	v_lshl_add_u64 v[2:3], s[0:1], 0, v[192:193]
	global_load_dwordx2 v[198:199], v[2:3], off offset:1024
	s_add_i32 s0, s30, s63
	s_add_i32 s0, s0, 0xfff80010
	s_ashr_i32 s4, s0, 2
	s_ashr_i32 s5, s4, 31
	s_lshl_b64 s[38:39], s[4:5], 8
	v_lshl_add_u64 v[200:201], v[190:191], 0, s[38:39]
	s_cmp_eq_i32 s63, -16
	s_cbranch_scc1 .Lkn6_s_1038_0_0
	s_waitcnt vmcnt(10)
	s_branch .Lkn6_e_1038_0_0

; __device__ __forceinline__ float bf2f(unsigned short u) { return __uint_as_float((unsigned)u << 16); }
; __device__ __forceinline__ unsigned f2bf(float f) { unsigned u = __float_as_uint(f); return (u + 0x7fffu + ((u >> 16) & 1u)) >> 16; }
; __device__ __forceinline__ void knorm_item(const KArgs& a, int l, int item, int wave, int lane) {
;     ...
;         for (int i = 0; i < 16; ++i) { const int task = item * 1024 + wave * 128 + r0 + i, row = task >> 2, which = (task >> 1) & 1, g = task & 1;
;             v[i] = bf2f(Z[(size_t)row * ZW + (which ? ZC_KW : ZC_KS) + g * 64 + lane]); }
; #pragma unroll
;         for (int i = 0; i < 16; ++i) { const int task = item * 1024 + wave * 128 + r0 + i, row = task >> 2, which = (task >> 1) & 1, g = task & 1;
;             const float rstd = rsqrtf(wave_sum(v[i] * v[i]) * (1.f / 64.f) + EPS);
;             bf16_t* dst = (bf16_t*)(a.ws + (which ? WS_KWN : WS_KSN));
;             dst[(size_t)row * 128 + g * 64 + lane] = (bf16_t)f2bf(v[i] * rstd * kg); }
.Lkn6_e_1038_0_0:
	v_lshlrev_b32_e32 v220, 16, v16
	v_and_b32_e32 v221, 0xffff0000, v16
	v_lshlrev_b32_e32 v222, 16, v17
	v_and_b32_e32 v223, 0xffff0000, v17
	v_lshlrev_b32_e32 v236, 16, v18
	v_and_b32_e32 v237, 0xffff0000, v18
	v_lshlrev_b32_e32 v238, 16, v19
	v_and_b32_e32 v239, 0xffff0000, v19
	v_mul_f32_e32 v224, v220, v220
	v_mul_f32_e32 v225, v221, v221
	v_mul_f32_e32 v226, v222, v222
	v_mul_f32_e32 v227, v223, v223
	v_mul_f32_e32 v240, v236, v236
	v_mul_f32_e32 v241, v237, v237
	v_mul_f32_e32 v242, v238, v238
	v_mul_f32_e32 v243, v239, v239
	v_fma_f32 v228, v220, v220, v225
	v_fma_f32 v229, v221, v221, v224
	v_fma_f32 v230, v222, v222, v227
	v_fma_f32 v231, v223, v223, v226
	v_fma_f32 v244, v236, v236, v241
	v_fma_f32 v245, v237, v237, v240
	v_fma_f32 v246, v238, v238, v243
	v_fma_f32 v247, v239, v239, v242
	v_add_f32_e32 v228, v228, v230
	v_add_f32_e32 v229, v229, v231
	v_add_f32_e32 v244, v244, v246
	v_add_f32_e32 v245, v245, v247
	v_add_f32_dpp v228, v228, v228 quad_perm:[1,0,3,2] row_mask:0xf bank_mask:0xf
	v_add_f32_dpp v229, v229, v229 quad_perm:[1,0,3,2] row_mask:0xf bank_mask:0xf
	v_add_f32_dpp v244, v244, v244 quad_perm:[1,0,3,2] row_mask:0xf bank_mask:0xf
	v_add_f32_dpp v245, v245, v245 quad_perm:[1,0,3,2] row_mask:0xf bank_mask:0xf
	v_add_f32_dpp v228, v228, v228 quad_perm:[2,3,0,1] row_mask:0xf bank_mask:0xf
	v_add_f32_dpp v229, v229, v229 quad_perm:[2,3,0,1] row_mask:0xf bank_mask:0xf
	v_add_f32_dpp v244, v244, v244 quad_perm:[2,3,0,1] row_mask:0xf bank_mask:0xf
	v_add_f32_dpp v245, v245, v245 quad_perm:[2,3,0,1] row_mask:0xf bank_mask:0xf
	ds_bpermute_b32 v230, v11, v228
	ds_bpermute_b32 v231, v11, v229
	ds_bpermute_b32 v246, v11, v244
	ds_bpermute_b32 v247, v11, v245
	s_waitcnt lgkmcnt(0)
	v_add_f32_e32 v228, v228, v230
	v_add_f32_e32 v229, v229, v231
	v_add_f32_e32 v244, v244, v246
	v_add_f32_e32 v245, v245, v247
	v_add_f32_dpp v228, v228, v228 row_ror:8 row_mask:0xf bank_mask:0xf
	v_add_f32_dpp v229, v229, v229 row_ror:8 row_mask:0xf bank_mask:0xf
	v_add_f32_dpp v244, v244, v244 row_ror:8 row_mask:0xf bank_mask:0xf
	v_add_f32_dpp v245, v245, v245 row_ror:8 row_mask:0xf bank_mask:0xf
	v_fma_f32 v228, v228, s28, v195
	v_fma_f32 v229, v229, s28, v195
	v_fma_f32 v244, v244, s28, v195
	v_fma_f32 v245, v245, s28, v195
	v_mul_f32_e32 v232, 0x4b800000, v228
	v_mul_f32_e32 v233, 0x4b800000, v229
	v_cmp_gt_f32_e64 s[4:5], s54, v228
	v_cmp_gt_f32_e32 vcc, s54, v229
	s_nop 1
	v_cndmask_b32_e64 v228, v228, v232, s[4:5]
	v_cndmask_b32_e32 v229, v229, v233, vcc
	v_rsq_f32_e32 v228, v228
	v_rsq_f32_e32 v229, v229
	s_nop 0
	v_mul_f32_e32 v232, 0x45800000, v228
	v_mul_f32_e32 v233, 0x45800000, v229
	v_cndmask_b32_e64 v228, v228, v232, s[4:5]
	v_cndmask_b32_e32 v229, v229, v233, vcc
	v_mul_f32_e32 v220, v228, v220
	v_mul_f32_e32 v221, v229, v221
	v_mul_f32_e32 v222, v228, v222
	v_mul_f32_e32 v223, v229, v223
	v_mul_f32_e32 v220, v184, v220
	v_mul_f32_e32 v221, v185, v221
	v_mul_f32_e32 v222, v186, v222
	v_mul_f32_e32 v223, v187, v223
	v_bfe_u32 v224, v220, 16, 1
	v_bfe_u32 v225, v221, 16, 1
	v_bfe_u32 v226, v222, 16, 1
	v_bfe_u32 v227, v223, 16, 1
	v_add3_u32 v220, v220, v224, s55
	v_add3_u32 v221, v221, v225, s55
	v_add3_u32 v222, v222, v226, s55
	v_add3_u32 v223, v223, v227, s55
	v_perm_b32 v234, v221, v220, v194
	v_perm_b32 v235, v223, v222, v194
	global_store_dwordx2 v[200:201], v[234:235], off
	v_mul_f32_e32 v248, 0x4b800000, v244
	v_mul_f32_e32 v249, 0x4b800000, v245
	v_cmp_gt_f32_e64 s[4:5], s54, v244
	v_cmp_gt_f32_e32 vcc, s54, v245
	s_nop 1
	v_cndmask_b32_e64 v244, v244, v248, s[4:5]
	v_cndmask_b32_e32 v245, v245, v249, vcc
	v_rsq_f32_e32 v244, v244
	v_rsq_f32_e32 v245, v245
	s_nop 0
	v_mul_f32_e32 v248, 0x45800000, v244
	v_mul_f32_e32 v249, 0x45800000, v245
	v_cndmask_b32_e64 v244, v244, v248, s[4:5]
	v_cndmask_b32_e32 v245, v245, v249, vcc
	v_mul_f32_e32 v236, v244, v236
	v_mul_f32_e32 v237, v245, v237
	v_mul_f32_e32 v238, v244, v238
	v_mul_f32_e32 v239, v245, v239
	v_mul_f32_e32 v236, v184, v236
	v_mul_f32_e32 v237, v185, v237
	v_mul_f32_e32 v238, v186, v238
	v_mul_f32_e32 v239, v187, v239
	v_bfe_u32 v240, v236, 16, 1
	v_bfe_u32 v241, v237, 16, 1
	v_bfe_u32 v242, v238, 16, 1
	v_bfe_u32 v243, v239, 16, 1
	v_add3_u32 v236, v236, v240, s55
	v_add3_u32 v237, v237, v241, s55
	v_add3_u32 v238, v238, v242, s55
	v_add3_u32 v239, v239, v243, s55
	v_perm_b32 v250, v237, v236, v194
	v_perm_b32 v251, v239, v238, v194
	global_store_dwordx2 v[200:201], v[250:251], off offset:256
	s_cmp_eq_i32 s63, -16
	s_cbranch_scc1 .Lkn6_s_1038_0_1
	s_waitcnt vmcnt(10)
	s_branch .Lkn6_e_1038_0_1

; __device__ __forceinline__ float bf2f(unsigned short u) { return __uint_as_float((unsigned)u << 16); }
; __device__ __forceinline__ unsigned f2bf(float f) { unsigned u = __float_as_uint(f); return (u + 0x7fffu + ((u >> 16) & 1u)) >> 16; }
; __device__ __forceinline__ void knorm_item(const KArgs& a, int l, int item, int wave, int lane) {
;     ...
;     for (int r0 = 0; r0 < 128; r0 += 16) {
;         float v[16];
; #pragma unroll
;         for (int i = 0; i < 16; ++i) { const int task = item * 1024 + wave * 128 + r0 + i, row = task >> 2, which = (task >> 1) & 1, g = task & 1;
;             v[i] = bf2f(Z[(size_t)row * ZW + (which ? ZC_KW : ZC_KS) + g * 64 + lane]); }
; #pragma unroll
;         for (int i = 0; i < 16; ++i) { const int task = item * 1024 + wave * 128 + r0 + i, row = task >> 2, which = (task >> 1) & 1, g = task & 1;
;             const float rstd = rsqrtf(wave_sum(v[i] * v[i]) * (1.f / 64.f) + EPS);
;             bf16_t* dst = (bf16_t*)(a.ws + (which ? WS_KWN : WS_KSN));
;             dst[(size_t)row * 128 + g * 64 + lane] = (bf16_t)f2bf(v[i] * rstd * kg); }
.Lkn6_e_1038_0_1:
	v_lshlrev_b32_e32 v220, 16, v20
	v_and_b32_e32 v221, 0xffff0000, v20
	v_lshlrev_b32_e32 v222, 16, v21
	v_and_b32_e32 v223, 0xffff0000, v21
	v_lshlrev_b32_e32 v236, 16, v22
	v_and_b32_e32 v237, 0xffff0000, v22
	v_lshlrev_b32_e32 v238, 16, v23
	v_and_b32_e32 v239, 0xffff0000, v23
	v_mul_f32_e32 v224, v220, v220
	v_mul_f32_e32 v225, v221, v221
	v_mul_f32_e32 v226, v222, v222
	v_mul_f32_e32 v227, v223, v223
	v_mul_f32_e32 v240, v236, v236
	v_mul_f32_e32 v241, v237, v237
	v_mul_f32_e32 v242, v238, v238
	v_mul_f32_e32 v243, v239, v239
	v_fma_f32 v228, v220, v220, v225
	v_fma_f32 v229, v221, v221, v224
	v_fma_f32 v230, v222, v222, v227
	v_fma_f32 v231, v223, v223, v226
	v_fma_f32 v244, v236, v236, v241
	v_fma_f32 v245, v237, v237, v240
	v_fma_f32 v246, v238, v238, v243
	v_fma_f32 v247, v239, v239, v242
	v_add_f32_e32 v228, v228, v230
	v_add_f32_e32 v229, v229, v231
	v_add_f32_e32 v244, v244, v246
	v_add_f32_e32 v245, v245, v247
	v_add_f32_dpp v228, v228, v228 quad_perm:[1,0,3,2] row_mask:0xf bank_mask:0xf
	v_add_f32_dpp v229, v229, v229 quad_perm:[1,0,3,2] row_mask:0xf bank_mask:0xf
	v_add_f32_dpp v244, v244, v244 quad_perm:[1,0,3,2] row_mask:0xf bank_mask:0xf
	v_add_f32_dpp v245, v245, v245 quad_perm:[1,0,3,2] row_mask:0xf bank_mask:0xf
	v_add_f32_dpp v228, v228, v228 quad_perm:[2,3,0,1] row_mask:0xf bank_mask:0xf
	v_add_f32_dpp v229, v229, v229 quad_perm:[2,3,0,1] row_mask:0xf bank_mask:0xf
	v_add_f32_dpp v244, v244, v244 quad_perm:[2,3,0,1] row_mask:0xf bank_mask:0xf
	v_add_f32_dpp v245, v245, v245 quad_perm:[2,3,0,1] row_mask:0xf bank_mask:0xf
	ds_bpermute_b32 v230, v11, v228
	ds_bpermute_b32 v231, v11, v229
	ds_bpermute_b32 v246, v11, v244
	ds_bpermute_b32 v247, v11, v245
	s_waitcnt lgkmcnt(0)
	v_add_f32_e32 v228, v228, v230
	v_add_f32_e32 v229, v229, v231
	v_add_f32_e32 v244, v244, v246
	v_add_f32_e32 v245, v245, v247
	v_add_f32_dpp v228, v228, v228 row_ror:8 row_mask:0xf bank_mask:0xf
	v_add_f32_dpp v229, v229, v229 row_ror:8 row_mask:0xf bank_mask:0xf
	v_add_f32_dpp v244, v244, v244 row_ror:8 row_mask:0xf bank_mask:0xf
	v_add_f32_dpp v245, v245, v245 row_ror:8 row_mask:0xf bank_mask:0xf
	v_fma_f32 v228, v228, s28, v195
	v_fma_f32 v229, v229, s28, v195
	v_fma_f32 v244, v244, s28, v195
	v_fma_f32 v245, v245, s28, v195
	v_mul_f32_e32 v232, 0x4b800000, v228
	v_mul_f32_e32 v233, 0x4b800000, v229
	v_cmp_gt_f32_e64 s[4:5], s54, v228
	v_cmp_gt_f32_e32 vcc, s54, v229
	s_nop 1
	v_cndmask_b32_e64 v228, v228, v232, s[4:5]
	v_cndmask_b32_e32 v229, v229, v233, vcc
	v_rsq_f32_e32 v228, v228
	v_rsq_f32_e32 v229, v229
	s_nop 0
	v_mul_f32_e32 v232, 0x45800000, v228
	v_mul_f32_e32 v233, 0x45800000, v229
	v_cndmask_b32_e64 v228, v228, v232, s[4:5]
	v_cndmask_b32_e32 v229, v229, v233, vcc
	v_mul_f32_e32 v220, v228, v220
	v_mul_f32_e32 v221, v229, v221
	v_mul_f32_e32 v222, v228, v222
	v_mul_f32_e32 v223, v229, v223
	v_mul_f32_e32 v220, v184, v220
	v_mul_f32_e32 v221, v185, v221
	v_mul_f32_e32 v222, v186, v222
	v_mul_f32_e32 v223, v187, v223
	v_bfe_u32 v224, v220, 16, 1
	v_bfe_u32 v225, v221, 16, 1
	v_bfe_u32 v226, v222, 16, 1
	v_bfe_u32 v227, v223, 16, 1
	v_add3_u32 v220, v220, v224, s55
	v_add3_u32 v221, v221, v225, s55
	v_add3_u32 v222, v222, v226, s55
	v_add3_u32 v223, v223, v227, s55
	v_perm_b32 v234, v221, v220, v194
	v_perm_b32 v235, v223, v222, v194
	global_store_dwordx2 v[200:201], v[234:235], off offset:512
	v_mul_f32_e32 v248, 0x4b800000, v244
	v_mul_f32_e32 v249, 0x4b800000, v245
	v_cmp_gt_f32_e64 s[4:5], s54, v244
	v_cmp_gt_f32_e32 vcc, s54, v245
	s_nop 1
	v_cndmask_b32_e64 v244, v244, v248, s[4:5]
	v_cndmask_b32_e32 v245, v245, v249, vcc
	v_rsq_f32_e32 v244, v244
	v_rsq_f32_e32 v245, v245
	s_nop 0
	v_mul_f32_e32 v248, 0x45800000, v244
	v_mul_f32_e32 v249, 0x45800000, v245
	v_cndmask_b32_e64 v244, v244, v248, s[4:5]
	v_cndmask_b32_e32 v245, v245, v249, vcc
	v_mul_f32_e32 v236, v244, v236
	v_mul_f32_e32 v237, v245, v237
	v_mul_f32_e32 v238, v244, v238
	v_mul_f32_e32 v239, v245, v239
	v_mul_f32_e32 v236, v184, v236
	v_mul_f32_e32 v237, v185, v237
	v_mul_f32_e32 v238, v186, v238
	v_mul_f32_e32 v239, v187, v239
	v_bfe_u32 v240, v236, 16, 1
	v_bfe_u32 v241, v237, 16, 1
	v_bfe_u32 v242, v238, 16, 1
	v_bfe_u32 v243, v239, 16, 1
	v_add3_u32 v236, v236, v240, s55
	v_add3_u32 v237, v237, v241, s55
	v_add3_u32 v238, v238, v242, s55
	v_add3_u32 v239, v239, v243, s55
	v_perm_b32 v250, v237, v236, v194
	v_perm_b32 v251, v239, v238, v194
	global_store_dwordx2 v[200:201], v[250:251], off offset:768
	s_cmpk_gt_i32 s63, 64
	s_cbranch_scc1 .Lkn6_skip_1038
	s_add_i32 s0, s30, s63
	s_add_i32 s0, s0, 0xfff80030
	s_ashr_i32 s4, s0, 2
	s_ashr_i32 s5, s4, 31
	s_mul_i32 s0, s4, 0x1a00
	s_mul_hi_i32 s1, s4, 0x1a00
	s_add_u32 s0, s92, s0
	s_addc_u32 s1, s93, s1
	v_lshl_add_u64 v[0:1], s[0:1], 0, v[192:193]
	global_load_dwordx2 v[16:17], v[0:1], off offset:1024
	s_add_u32 s0, s0, 0x1a00
	s_addc_u32 s1, s1, 0
	v_lshl_add_u64 v[2:3], s[0:1], 0, v[192:193]
	global_load_dwordx2 v[18:19], v[2:3], off offset:1024
	s_add_u32 s0, s0, 0x1a00
	s_addc_u32 s1, s1, 0
	v_lshl_add_u64 v[0:1], s[0:1], 0, v[192:193]
	global_load_dwordx2 v[20:21], v[0:1], off offset:1024
	s_add_u32 s0, s0, 0x1a00
	s_addc_u32 s1, s1, 0
	v_lshl_add_u64 v[2:3], s[0:1], 0, v[192:193]
	global_load_dwordx2 v[22:23], v[2:3], off offset:1024
.Lkn6_skip_1038:
	s_add_i32 s0, s30, s63
	s_add_i32 s0, s0, 0xfff80020
	s_ashr_i32 s4, s0, 2
	s_ashr_i32 s5, s4, 31
	s_lshl_b64 s[38:39], s[4:5], 8
	v_lshl_add_u64 v[200:201], v[190:191], 0, s[38:39]
	s_cmpk_eq_i32 s63, 0x50
	s_cbranch_scc1 .Lkn6_s_1038_1_0
	s_waitcnt vmcnt(10)
	s_branch .Lkn6_e_1038_1_0

; __device__ __forceinline__ float bf2f(unsigned short u) { return __uint_as_float((unsigned)u << 16); }
; __device__ __forceinline__ unsigned f2bf(float f) { unsigned u = __float_as_uint(f); return (u + 0x7fffu + ((u >> 16) & 1u)) >> 16; }
; __device__ __forceinline__ void knorm_item(const KArgs& a, int l, int item, int wave, int lane) {
;     ...
;         for (int i = 0; i < 16; ++i) { const int task = item * 1024 + wave * 128 + r0 + i, row = task >> 2, which = (task >> 1) & 1, g = task & 1;
;             v[i] = bf2f(Z[(size_t)row * ZW + (which ? ZC_KW : ZC_KS) + g * 64 + lane]); }
; #pragma unroll
;         for (int i = 0; i < 16; ++i) { const int task = item * 1024 + wave * 128 + r0 + i, row = task >> 2, which = (task >> 1) & 1, g = task & 1;
;             const float rstd = rsqrtf(wave_sum(v[i] * v[i]) * (1.f / 64.f) + EPS);
;             bf16_t* dst = (bf16_t*)(a.ws + (which ? WS_KWN : WS_KSN));
;             dst[(size_t)row * 128 + g * 64 + lane] = (bf16_t)f2bf(v[i] * rstd * kg); }
.Lkn6_e_1038_1_0:
	v_lshlrev_b32_e32 v220, 16, v24
	v_and_b32_e32 v221, 0xffff0000, v24
	v_lshlrev_b32_e32 v222, 16, v25
	v_and_b32_e32 v223, 0xffff0000, v25
	v_lshlrev_b32_e32 v236, 16, v26
	v_and_b32_e32 v237, 0xffff0000, v26
	v_lshlrev_b32_e32 v238, 16, v27
	v_and_b32_e32 v239, 0xffff0000, v27
	v_mul_f32_e32 v224, v220, v220
	v_mul_f32_e32 v225, v221, v221
	v_mul_f32_e32 v226, v222, v222
	v_mul_f32_e32 v227, v223, v223
	v_mul_f32_e32 v240, v236, v236
	v_mul_f32_e32 v241, v237, v237
	v_mul_f32_e32 v242, v238, v238
	v_mul_f32_e32 v243, v239, v239
	v_fma_f32 v228, v220, v220, v225
	v_fma_f32 v229, v221, v221, v224
	v_fma_f32 v230, v222, v222, v227
	v_fma_f32 v231, v223, v223, v226
	v_fma_f32 v244, v236, v236, v241
	v_fma_f32 v245, v237, v237, v240
	v_fma_f32 v246, v238, v238, v243
	v_fma_f32 v247, v239, v239, v242
	v_add_f32_e32 v228, v228, v230
	v_add_f32_e32 v229, v229, v231
	v_add_f32_e32 v244, v244, v246
	v_add_f32_e32 v245, v245, v247
	v_add_f32_dpp v228, v228, v228 quad_perm:[1,0,3,2] row_mask:0xf bank_mask:0xf
	v_add_f32_dpp v229, v229, v229 quad_perm:[1,0,3,2] row_mask:0xf bank_mask:0xf
	v_add_f32_dpp v244, v244, v244 quad_perm:[1,0,3,2] row_mask:0xf bank_mask:0xf
	v_add_f32_dpp v245, v245, v245 quad_perm:[1,0,3,2] row_mask:0xf bank_mask:0xf
	v_add_f32_dpp v228, v228, v228 quad_perm:[2,3,0,1] row_mask:0xf bank_mask:0xf
	v_add_f32_dpp v229, v229, v229 quad_perm:[2,3,0,1] row_mask:0xf bank_mask:0xf
	v_add_f32_dpp v244, v244, v244 quad_perm:[2,3,0,1] row_mask:0xf bank_mask:0xf
	v_add_f32_dpp v245, v245, v245 quad_perm:[2,3,0,1] row_mask:0xf bank_mask:0xf
	ds_bpermute_b32 v230, v11, v228
	ds_bpermute_b32 v231, v11, v229
	ds_bpermute_b32 v246, v11, v244
	ds_bpermute_b32 v247, v11, v245
	s_waitcnt lgkmcnt(0)
	v_add_f32_e32 v228, v228, v230
	v_add_f32_e32 v229, v229, v231
	v_add_f32_e32 v244, v244, v246
	v_add_f32_e32 v245, v245, v247
	v_add_f32_dpp v228, v228, v228 row_ror:8 row_mask:0xf bank_mask:0xf
	v_add_f32_dpp v229, v229, v229 row_ror:8 row_mask:0xf bank_mask:0xf
	v_add_f32_dpp v244, v244, v244 row_ror:8 row_mask:0xf bank_mask:0xf
	v_add_f32_dpp v245, v245, v245 row_ror:8 row_mask:0xf bank_mask:0xf
	v_fma_f32 v228, v228, s28, v195
	v_fma_f32 v229, v229, s28, v195
	v_fma_f32 v244, v244, s28, v195
	v_fma_f32 v245, v245, s28, v195
	v_mul_f32_e32 v232, 0x4b800000, v228
	v_mul_f32_e32 v233, 0x4b800000, v229
	v_cmp_gt_f32_e64 s[4:5], s54, v228
	v_cmp_gt_f32_e32 vcc, s54, v229
	s_nop 1
	v_cndmask_b32_e64 v228, v228, v232, s[4:5]
	v_cndmask_b32_e32 v229, v229, v233, vcc
	v_rsq_f32_e32 v228, v228
	v_rsq_f32_e32 v229, v229
	s_nop 0
	v_mul_f32_e32 v232, 0x45800000, v228
	v_mul_f32_e32 v233, 0x45800000, v229
	v_cndmask_b32_e64 v228, v228, v232, s[4:5]
	v_cndmask_b32_e32 v229, v229, v233, vcc
	v_mul_f32_e32 v220, v228, v220
	v_mul_f32_e32 v221, v229, v221
	v_mul_f32_e32 v222, v228, v222
	v_mul_f32_e32 v223, v229, v223
	v_mul_f32_e32 v220, v184, v220
	v_mul_f32_e32 v221, v185, v221
	v_mul_f32_e32 v222, v186, v222
	v_mul_f32_e32 v223, v187, v223
	v_bfe_u32 v224, v220, 16, 1
	v_bfe_u32 v225, v221, 16, 1
	v_bfe_u32 v226, v222, 16, 1
	v_bfe_u32 v227, v223, 16, 1
	v_add3_u32 v220, v220, v224, s55
	v_add3_u32 v221, v221, v225, s55
	v_add3_u32 v222, v222, v226, s55
	v_add3_u32 v223, v223, v227, s55
	v_perm_b32 v234, v221, v220, v194
	v_perm_b32 v235, v223, v222, v194
	global_store_dwordx2 v[200:201], v[234:235], off
	v_mul_f32_e32 v248, 0x4b800000, v244
	v_mul_f32_e32 v249, 0x4b800000, v245
	v_cmp_gt_f32_e64 s[4:5], s54, v244
	v_cmp_gt_f32_e32 vcc, s54, v245
	s_nop 1
	v_cndmask_b32_e64 v244, v244, v248, s[4:5]
	v_cndmask_b32_e32 v245, v245, v249, vcc
	v_rsq_f32_e32 v244, v244
	v_rsq_f32_e32 v245, v245
	s_nop 0
	v_mul_f32_e32 v248, 0x45800000, v244
	v_mul_f32_e32 v249, 0x45800000, v245
	v_cndmask_b32_e64 v244, v244, v248, s[4:5]
	v_cndmask_b32_e32 v245, v245, v249, vcc
	v_mul_f32_e32 v236, v244, v236
	v_mul_f32_e32 v237, v245, v237
	v_mul_f32_e32 v238, v244, v238
	v_mul_f32_e32 v239, v245, v239
	v_mul_f32_e32 v236, v184, v236
	v_mul_f32_e32 v237, v185, v237
	v_mul_f32_e32 v238, v186, v238
	v_mul_f32_e32 v239, v187, v239
	v_bfe_u32 v240, v236, 16, 1
	v_bfe_u32 v241, v237, 16, 1
	v_bfe_u32 v242, v238, 16, 1
	v_bfe_u32 v243, v239, 16, 1
	v_add3_u32 v236, v236, v240, s55
	v_add3_u32 v237, v237, v241, s55
	v_add3_u32 v238, v238, v242, s55
	v_add3_u32 v239, v239, v243, s55
	v_perm_b32 v250, v237, v236, v194
	v_perm_b32 v251, v239, v238, v194
	global_store_dwordx2 v[200:201], v[250:251], off offset:256
	s_cmpk_eq_i32 s63, 0x50
	s_cbranch_scc1 .Lkn6_s_1038_1_1
	s_waitcnt vmcnt(10)
	s_branch .Lkn6_e_1038_1_1

; __device__ __forceinline__ float bf2f(unsigned short u) { return __uint_as_float((unsigned)u << 16); }
; __device__ __forceinline__ unsigned f2bf(float f) { unsigned u = __float_as_uint(f); return (u + 0x7fffu + ((u >> 16) & 1u)) >> 16; }
; __device__ __forceinline__ void knorm_item(const KArgs& a, int l, int item, int wave, int lane) {
;     ...
;         for (int i = 0; i < 16; ++i) { const int task = item * 1024 + wave * 128 + r0 + i, row = task >> 2, which = (task >> 1) & 1, g = task & 1;
;             v[i] = bf2f(Z[(size_t)row * ZW + (which ? ZC_KW : ZC_KS) + g * 64 + lane]); }
; #pragma unroll
;         for (int i = 0; i < 16; ++i) { const int task = item * 1024 + wave * 128 + r0 + i, row = task >> 2, which = (task >> 1) & 1, g = task & 1;
;             const float rstd = rsqrtf(wave_sum(v[i] * v[i]) * (1.f / 64.f) + EPS);
;             bf16_t* dst = (bf16_t*)(a.ws + (which ? WS_KWN : WS_KSN));
;             dst[(size_t)row * 128 + g * 64 + lane] = (bf16_t)f2bf(v[i] * rstd * kg); }
.Lkn6_e_1038_1_1:
	v_lshlrev_b32_e32 v220, 16, v196
	v_and_b32_e32 v221, 0xffff0000, v196
	v_lshlrev_b32_e32 v222, 16, v197
	v_and_b32_e32 v223, 0xffff0000, v197
	v_lshlrev_b32_e32 v236, 16, v198
	v_and_b32_e32 v237, 0xffff0000, v198
	v_lshlrev_b32_e32 v238, 16, v199
	v_and_b32_e32 v239, 0xffff0000, v199
	v_mul_f32_e32 v224, v220, v220
	v_mul_f32_e32 v225, v221, v221
	v_mul_f32_e32 v226, v222, v222
	v_mul_f32_e32 v227, v223, v223
	v_mul_f32_e32 v240, v236, v236
	v_mul_f32_e32 v241, v237, v237
	v_mul_f32_e32 v242, v238, v238
	v_mul_f32_e32 v243, v239, v239
	v_fma_f32 v228, v220, v220, v225
	v_fma_f32 v229, v221, v221, v224
	v_fma_f32 v230, v222, v222, v227
	v_fma_f32 v231, v223, v223, v226
	v_fma_f32 v244, v236, v236, v241
	v_fma_f32 v245, v237, v237, v240
	v_fma_f32 v246, v238, v238, v243
	v_fma_f32 v247, v239, v239, v242
	v_add_f32_e32 v228, v228, v230
	v_add_f32_e32 v229, v229, v231
	v_add_f32_e32 v244, v244, v246
	v_add_f32_e32 v245, v245, v247
	v_add_f32_dpp v228, v228, v228 quad_perm:[1,0,3,2] row_mask:0xf bank_mask:0xf
	v_add_f32_dpp v229, v229, v229 quad_perm:[1,0,3,2] row_mask:0xf bank_mask:0xf
	v_add_f32_dpp v244, v244, v244 quad_perm:[1,0,3,2] row_mask:0xf bank_mask:0xf
	v_add_f32_dpp v245, v245, v245 quad_perm:[1,0,3,2] row_mask:0xf bank_mask:0xf
	v_add_f32_dpp v228, v228, v228 quad_perm:[2,3,0,1] row_mask:0xf bank_mask:0xf
	v_add_f32_dpp v229, v229, v229 quad_perm:[2,3,0,1] row_mask:0xf bank_mask:0xf
	v_add_f32_dpp v244, v244, v244 quad_perm:[2,3,0,1] row_mask:0xf bank_mask:0xf
	v_add_f32_dpp v245, v245, v245 quad_perm:[2,3,0,1] row_mask:0xf bank_mask:0xf
	ds_bpermute_b32 v230, v11, v228
	ds_bpermute_b32 v231, v11, v229
	ds_bpermute_b32 v246, v11, v244
	ds_bpermute_b32 v247, v11, v245
	s_waitcnt lgkmcnt(0)
	v_add_f32_e32 v228, v228, v230
	v_add_f32_e32 v229, v229, v231
	v_add_f32_e32 v244, v244, v246
	v_add_f32_e32 v245, v245, v247
	v_add_f32_dpp v228, v228, v228 row_ror:8 row_mask:0xf bank_mask:0xf
	v_add_f32_dpp v229, v229, v229 row_ror:8 row_mask:0xf bank_mask:0xf
	v_add_f32_dpp v244, v244, v244 row_ror:8 row_mask:0xf bank_mask:0xf
	v_add_f32_dpp v245, v245, v245 row_ror:8 row_mask:0xf bank_mask:0xf
	v_fma_f32 v228, v228, s28, v195
	v_fma_f32 v229, v229, s28, v195
	v_fma_f32 v244, v244, s28, v195
	v_fma_f32 v245, v245, s28, v195
	v_mul_f32_e32 v232, 0x4b800000, v228
	v_mul_f32_e32 v233, 0x4b800000, v229
	v_cmp_gt_f32_e64 s[4:5], s54, v228
	v_cmp_gt_f32_e32 vcc, s54, v229
	s_nop 1
	v_cndmask_b32_e64 v228, v228, v232, s[4:5]
	v_cndmask_b32_e32 v229, v229, v233, vcc
	v_rsq_f32_e32 v228, v228
	v_rsq_f32_e32 v229, v229
	s_nop 0
	v_mul_f32_e32 v232, 0x45800000, v228
	v_mul_f32_e32 v233, 0x45800000, v229
	v_cndmask_b32_e64 v228, v228, v232, s[4:5]
	v_cndmask_b32_e32 v229, v229, v233, vcc
	v_mul_f32_e32 v220, v228, v220
	v_mul_f32_e32 v221, v229, v221
	v_mul_f32_e32 v222, v228, v222
	v_mul_f32_e32 v223, v229, v223
	v_mul_f32_e32 v220, v184, v220
	v_mul_f32_e32 v221, v185, v221
	v_mul_f32_e32 v222, v186, v222
	v_mul_f32_e32 v223, v187, v223
	v_bfe_u32 v224, v220, 16, 1
	v_bfe_u32 v225, v221, 16, 1
	v_bfe_u32 v226, v222, 16, 1
	v_bfe_u32 v227, v223, 16, 1
	v_add3_u32 v220, v220, v224, s55
	v_add3_u32 v221, v221, v225, s55
	v_add3_u32 v222, v222, v226, s55
	v_add3_u32 v223, v223, v227, s55
	v_perm_b32 v234, v221, v220, v194
	v_perm_b32 v235, v223, v222, v194
	global_store_dwordx2 v[200:201], v[234:235], off offset:512
	v_mul_f32_e32 v248, 0x4b800000, v244
	v_mul_f32_e32 v249, 0x4b800000, v245
	v_cmp_gt_f32_e64 s[4:5], s54, v244
	v_cmp_gt_f32_e32 vcc, s54, v245
	s_nop 1
	v_cndmask_b32_e64 v244, v244, v248, s[4:5]
	v_cndmask_b32_e32 v245, v245, v249, vcc
	v_rsq_f32_e32 v244, v244
	v_rsq_f32_e32 v245, v245
	s_nop 0
	v_mul_f32_e32 v248, 0x45800000, v244
	v_mul_f32_e32 v249, 0x45800000, v245
	v_cndmask_b32_e64 v244, v244, v248, s[4:5]
	v_cndmask_b32_e32 v245, v245, v249, vcc
	v_mul_f32_e32 v236, v244, v236
	v_mul_f32_e32 v237, v245, v237
	v_mul_f32_e32 v238, v244, v238
	v_mul_f32_e32 v239, v245, v239
	v_mul_f32_e32 v236, v184, v236
	v_mul_f32_e32 v237, v185, v237
	v_mul_f32_e32 v238, v186, v238
	v_mul_f32_e32 v239, v187, v239
	v_bfe_u32 v240, v236, 16, 1
	v_bfe_u32 v241, v237, 16, 1
	v_bfe_u32 v242, v238, 16, 1
	v_bfe_u32 v243, v239, 16, 1
	v_add3_u32 v236, v236, v240, s55
	v_add3_u32 v237, v237, v241, s55
	v_add3_u32 v238, v238, v242, s55
	v_add3_u32 v239, v239, v243, s55
	v_perm_b32 v250, v237, v236, v194
	v_perm_b32 v251, v239, v238, v194
	global_store_dwordx2 v[200:201], v[250:251], off offset:768
	s_add_i32 s63, s63, 32
	s_cmpk_gt_u32 s63, 0x6f
	s_cbranch_scc0 .LBB0_1038
	s_mov_b64 s[0:1], 0
